# Affo tail conversion moved from P2 to P1 idle-slot WGs; barrier poll s_sleep 12/6 -> 2
# speedup vs baseline: 1.0029x; 1.0012x over previous
.LBB0_121:
	s_and_b32 s17, s16, 0xff
	s_mov_b64 s[30:31], -1
	s_cmp_lg_u32 s17, 0
	s_mov_b64 s[38:39], -1
	s_sleep 2
	s_cbranch_scc0 .LBB0_124
	s_and_b64 vcc, exec, s[38:39]
	s_cbranch_vccz .LBB0_120

.LBB0_138:
	s_and_b32 s17, s16, 0xff
	s_cmp_lg_u32 s17, 0
	s_mov_b64 s[36:37], -1
	s_sleep 2
	s_cbranch_scc0 .LBB0_141
	s_mov_b64 s[38:39], -1
	s_and_b64 vcc, exec, s[36:37]
	s_cbranch_vccz .LBB0_137

.LBB0_387:
	s_and_b32 s17, s16, 0xff
	s_mov_b64 s[38:39], -1
	s_cmp_lg_u32 s17, 0
	s_mov_b64 s[42:43], -1
	s_sleep 2
	s_cbranch_scc0 .LBB0_390
	s_and_b64 vcc, exec, s[42:43]
	s_cbranch_vccz .LBB0_386

.LBB0_404:
	s_and_b32 s17, s16, 0xff
	s_cmp_lg_u32 s17, 0
	s_mov_b64 s[40:41], -1
	s_sleep 2
	s_cbranch_scc0 .LBB0_407
	s_mov_b64 s[42:43], -1
	s_and_b64 vcc, exec, s[40:41]
	s_cbranch_vccz .LBB0_403

.LBB0_422:
	s_and_b32 s17, s16, 63
	s_cmp_lg_u32 s17, 0
	s_mov_b64 s[36:37], -1
	s_sleep 2
	s_cbranch_scc0 .LBB0_425
	s_mov_b64 s[38:39], -1
	s_and_b64 vcc, exec, s[36:37]
	s_cbranch_vccz .LBB0_421

.LBB0_634:
	s_and_b32 s17, s16, 0xff
	s_mov_b64 s[28:29], -1
	s_cmp_lg_u32 s17, 0
	s_mov_b64 s[36:37], -1
	s_sleep 2
	s_cbranch_scc0 .LBB0_637
	s_and_b64 vcc, exec, s[36:37]
	s_cbranch_vccz .LBB0_633

.LBB0_651:
	s_and_b32 s17, s16, 0xff
	s_cmp_lg_u32 s17, 0
	s_mov_b64 s[30:31], -1
	s_sleep 2
	s_cbranch_scc0 .LBB0_654
	s_mov_b64 s[36:37], -1
	s_and_b64 vcc, exec, s[30:31]
	s_cbranch_vccz .LBB0_650

.LBB0_669:
	s_and_b32 s17, s16, 63
	s_cmp_lg_u32 s17, 0
	s_mov_b64 s[24:25], -1
	s_sleep 2
	s_cbranch_scc0 .LBB0_672
	s_mov_b64 s[28:29], -1
	s_and_b64 vcc, exec, s[24:25]
	s_cbranch_vccz .LBB0_668

.LBB0_1015:
	s_and_b32 s17, s16, 0xff
	s_mov_b64 s[24:25], -1
	s_cmp_lg_u32 s17, 0
	s_mov_b64 s[30:31], -1
	s_sleep 2
	s_cbranch_scc0 .LBB0_1018
	s_and_b64 vcc, exec, s[30:31]
	s_cbranch_vccz .LBB0_1014

.LBB0_1032:
	s_and_b32 s17, s16, 0xff
	s_cmp_lg_u32 s17, 0
	s_mov_b64 s[28:29], -1
	s_sleep 2
	s_cbranch_scc0 .LBB0_1035
	s_mov_b64 s[30:31], -1
	s_and_b64 vcc, exec, s[28:29]
	s_cbranch_vccz .LBB0_1031

.LBB0_1976:
	s_and_b32 s22, s26, 0xff
	s_mov_b64 s[20:21], -1
	s_cmp_lg_u32 s22, 0
	s_mov_b64 s[24:25], -1
	s_sleep 2
	s_cbranch_scc0 .LBB0_1979
	s_and_b64 vcc, exec, s[24:25]
	s_cbranch_vccz .LBB0_1975

.LBB0_1993:
	s_and_b32 s20, s26, 0xff
	s_cmp_lg_u32 s20, 0
	s_mov_b64 s[22:23], -1
	s_sleep 2
	s_cbranch_scc0 .LBB0_1996
	s_mov_b64 s[24:25], -1
	s_and_b64 vcc, exec, s[22:23]
	s_cbranch_vccz .LBB0_1992
